# gMLP task: LayerNorm-stat loads of the 4 row chunks issued together, LN gamma/beta loads hoisted out of the 8 normalise blocks, u/gate loads of all 4 chunks prefetched before the first MFMA loop
# speedup vs baseline: 1.0011x; 1.0011x over previous
; #define LAS __attribute__((address_space(3)))
; __device__ __forceinline__ int lane_fresh() { int l; asm volatile("v_mbcnt_lo_u32_b32 %0, -1, 0\n\tv_mbcnt_hi_u32_b32 %0, -1, %0" : "=v"(l)); return l; }
; __device__ __forceinline__ void attn_run(LAS unsigned char* lds, const Params& p, const bf16_t* P, bf16_t* Y, float* ssa, int l, int t0, int t1, int wave) {
;     ...
;     const int lane = lane_fresh(), tid = wave * 64 + lane;
;     LAS bf16_t* KS = (LAS bf16_t*)(lds + L_KS);
;     LAS bf16_t* VT = (LAS bf16_t*)(lds + L_VT);
;     const LAS float* BIAS = (const LAS float*)(lds + L_BIAS);
;     const int r = lane & 31, h = lane >> 5;
;     const int jk = tid >> 3, chk = tid & 7;
;     const int jv = jk, chv = chk;
;     u32x4 pk = (u32x4){0u, 0u, 0u, 0u}, pv = pk;
;     bf16x8 qn[4];
; #pragma unroll
;     for (int s = 0; s < 4; ++s) qn[s] = (bf16x8){0, 0, 0, 0, 0, 0, 0, 0};
;     int prev_bk = -1, prev_c = -100;
; __device__ __forceinline__ void p2_phase(LAS unsigned char* lds, const Params& p, int l, int tid, int wave, int lane, int bid, int G) {
;     ...
;     else { const int rest = 3072 - ngemm * xg, nb = 256 - ngemm, q = rest / nb, rem = rest - q * nb, j = bid - ngemm; start = ngemm * xg + j * q + (j < rem ? j : rem); count = q + (j < rem ? 1 : 0); }
;     const int end = start + count;
;     const int ta0 = 2 * (start / 3) + (start % 3 < 2 ? start % 3 : 2), ta1 = 2 * (end / 3) + (end % 3 < 2 ? end % 3 : 2), ug0 = start / 3, ug1 = end / 3;
;     const int tsplit = (bid < 32) ? (ta0 + 2 < ta1 ? ta0 + 2 : ta1) : ta1;
;     attn_run(lds, p, P, Y, SSA, l, ta0, tsplit, wave);
.LBB0_322:
	s_mul_hi_i32 s20, s12, 0x55555556
	s_lshr_b32 s1, s20, 31
	s_add_i32 s20, s20, s1
	s_add_i32 s0, s12, s13
	s_mul_i32 s7, s20, 3
	s_lshl_b32 s1, s20, 1
	s_sub_i32 s7, s12, s7
	s_mul_hi_i32 s21, s0, 0x55555556
	s_add_i32 s7, s1, s7
	s_lshr_b32 s1, s21, 31
	s_add_i32 s21, s21, s1
	s_mul_i32 s1, s21, 3
	s_lshl_b32 s16, s21, 1
	s_sub_i32 s0, s0, s1
	s_add_i32 s16, s16, s0
	s_add_i32 s0, s7, 2
	s_min_i32 s10, s0, s16
	v_readlane_b32 s0, v253, 19
	v_readlane_b32 s1, v253, 20
	s_and_b64 s[0:1], s[0:1], exec
	s_cselect_b32 s17, s10, s16
	s_cmp_ge_i32 s7, s17
	s_cbranch_scc1 .LBB0_361
	v_xor_b32_e32 v6, 32, v185
	v_mbcnt_lo_u32_b32 v0, -1, 0
	v_mbcnt_hi_u32_b32 v0, -1, v0
	v_cmp_lt_i32_e32 vcc, v6, v186
	v_add_u32_e32 v2, s6, v0
	v_ashrrev_i32_e32 v152, 3, v2
	v_ashrrev_i32_e32 v2, 5, v0
	v_cndmask_b32_e32 v6, v185, v6, vcc
	v_lshlrev_b32_e32 v156, 3, v2
	v_lshlrev_b32_e32 v5, 4, v2
	v_lshlrev_b32_e32 v2, 2, v2
	v_lshlrev_b32_e32 v167, 2, v6
	v_lshrrev_b32_e32 v6, 2, v0
	v_and_b32_e32 v155, 31, v0
	v_lshlrev_b32_e32 v3, 3, v0
	v_readlane_b32 s0, v253, 25
	v_and_or_b32 v168, v6, 3, v2
	v_and_b32_e32 v2, 16, v0
	v_and_b32_e32 v4, 56, v3
	v_or_b32_e32 v159, s0, v155
	v_lshlrev_b32_e32 v2, 1, v2
	v_and_b32_e32 v3, 24, v3
	v_readlane_b32 s0, v255, 13
	v_add3_u32 v158, 0, v2, v3
	v_lshlrev_b32_e32 v2, 2, v159
	v_readlane_b32 s1, v255, 14
	s_lshl_b32 s18, s0, 4
	v_sub_u32_e32 v2, 0, v2
	s_mov_b32 s0, 0x20000
	v_add3_u32 v170, v2, v5, s0
	v_mad_i64_i32 v[2:3], s[0:1], v152, s73, 0
	v_cmp_gt_u32_e64 s[40:41], 32, v0
	v_and_b32_e32 v0, 7, v0
	v_readlane_b32 s0, v254, 28
	v_lshl_or_b32 v2, v0, 4, v2
	v_readlane_b32 s1, v254, 29
	v_mov_b32_e32 v100, v1
	v_mov_b32_e32 v101, v1
	v_lshl_add_u64 v[160:161], s[0:1], 0, v[2:3]
	v_mov_b32_e32 v2, v1
	v_mov_b32_e32 v3, v1
	v_mov_b32_e32 v0, v1
	v_mov_b32_e32 v98, v1
	v_mov_b32_e32 v99, v1
	v_mov_b64_e32 v[112:113], v[100:101]
	v_mov_b64_e32 v[116:117], v[100:101]
	v_mov_b64_e32 v[120:121], v[100:101]
	v_mov_b64_e32 v[104:105], v[2:3]
	v_mov_b64_e32 v[108:109], v[2:3]
	v_ashrrev_i32_e32 v153, 31, v152
	v_lshl_add_u32 v154, v4, 1, 0
	v_ashrrev_i32_e32 v157, 31, v156
	v_add_u32_e32 v166, 0, v5
	s_mov_b32 s19, -1
	v_add_u32_e32 v169, 32, v168
	s_sub_i32 s22, s12, s20
	s_movk_i32 s23, 0xff9c
	v_lshlrev_b32_e32 v162, 1, v4
	v_mov_b64_e32 v[110:111], v[98:99]
	v_mov_b64_e32 v[114:115], v[98:99]
	v_mov_b64_e32 v[118:119], v[98:99]
	v_mov_b64_e32 v[102:103], v[0:1]
	v_mov_b64_e32 v[106:107], v[0:1]
	s_branch .LBB0_325

; #define LAS __attribute__((address_space(3)))
; __device__ __forceinline__ u32x4 pack8(f32x4 a, f32x4 b) { u32x4 w; w.x = pk2(a[0], a[1]); w.y = pk2(a[2], a[3]); w.z = pk2(b[0], b[1]); w.w = pk2(b[2], b[3]); return w; }
; __device__ __forceinline__ void gmlp_task(LAS unsigned char* lds, const Params& p, const bf16_t* P, bf16_t* Y, const float* svg, float* ssb, int l, bool sample, int b, int g, int q, int tid, int wave, int lane, bool load_ws = true) {
;     ...
;     for (int sub = 0; sub < 4; ++sub) {
;         const int cidx = q * 4 + sub;
;         const size_t row0 = sample ? (size_t)NP + cidx * 32 : (size_t)b * 2048 + cidx * 128;
;         if ((tid >> 2) < L) {
;             const int j = tid >> 2, qq = tid & 3;
;             const f32x4* sp = (const f32x4*)(svg + ((row0 + j) * 16 + qq * 4) * 2);
;             const f32x4 a = sp[0], bq = sp[1];
;             float s1 = (a[0] + a[2]) + (bq[0] + bq[2]), s2 = (a[1] + a[3]) + (bq[1] + bq[3]);
;             s1 += __shfl_xor(s1, 1); s1 += __shfl_xor(s1, 2); s2 += __shfl_xor(s2, 1); s2 += __shfl_xor(s2, 2);
;             const float mean = s1 * (1.0f / 1024.0f), var = s2 * (1.0f / 1024.0f) - mean * mean;
;             if (qq == 0) MUR[sub * 128 + j] = (f32x2){mean, __builtin_amdgcn_rsqf(var + EPS)};
;         }
;     }
;     ...
; #pragma unroll
;         for (int k = 0; k < 2; ++k) {
;             const int id = tid + 512 * k;
;             if (id >= L * 8) continue;
;             const int ch = id & 7, j = id >> 3;
;             const f32x2 mr = MUR[sub * 128 + j];
;             const float mean = mr.x, rstd = mr.y;
;             const u32x4 w = wraw[sub][k];
;             const f32x4 g0 = *(const f32x4*)(lg + ch * 8), g1 = *(const f32x4*)(lg + ch * 8 + 4), b0 = *(const f32x4*)(lb + ch * 8), b1 = *(const f32x4*)(lb + ch * 8 + 4);
;             f32x4 v0 = (f32x4){bf_lo(w.x), bf_hi(w.x), bf_lo(w.y), bf_hi(w.y)}, v1 = (f32x4){bf_lo(w.z), bf_hi(w.z), bf_lo(w.w), bf_hi(w.w)};
;             v0 = (v0 - mean) * rstd * g0 + b0; v1 = (v1 - mean) * rstd * g1 + b1;
;             if (sample) { float* dst = p.out + OUT_VGS + ((((size_t)l * 32 + cidx) * 32 + j) * 16 + g) * 64 + ch * 8; *(f32x4*)dst = v0; *(f32x4*)(dst + 4) = v1; }
;             *(LAS u32x4*)(VGT + j * 72 + ch * 8) = pack8(v0, v1);
.LBB0_469:
	s_or_b64 exec, exec, s[16:17]
	v_ashrrev_i32_e32 v34, 2, v44
	s_movk_i32 s16, 0x80
	v_cmp_gt_i32_e32 vcc, s16, v34
	v_and_b32_e32 v45, 3, v42
	s_and_saveexec_b64 s[16:17], vcc
	s_cbranch_execz .LBB0_478
	v_ashrrev_i32_e32 v35, 31, v34
	v_lshlrev_b32_e32 v0, 5, v45
	v_lshl_add_u64 v[36:37], s[82:83], 0, v[0:1]
	v_lshl_add_u64 v[38:39], v[34:35], 0, s[44:45]
	v_lshlrev_b64 v[38:39], 7, v[38:39]
	v_lshl_add_u64 v[48:49], v[36:37], 0, v[38:39]
	global_load_dwordx4 v[192:195], v[48:49], off
	global_load_dwordx4 v[196:199], v[48:49], off offset:16
	v_lshl_add_u64 v[38:39], v[34:35], 0, s[14:15]
	v_lshlrev_b64 v[38:39], 7, v[38:39]
	v_lshl_add_u64 v[48:49], v[36:37], 0, v[38:39]
	global_load_dwordx4 v[200:203], v[48:49], off
	global_load_dwordx4 v[204:207], v[48:49], off offset:16
	v_lshl_add_u64 v[38:39], v[34:35], 0, s[12:13]
	v_lshlrev_b64 v[38:39], 7, v[38:39]
	v_lshl_add_u64 v[48:49], v[36:37], 0, v[38:39]
	global_load_dwordx4 v[208:211], v[48:49], off
	global_load_dwordx4 v[212:215], v[48:49], off offset:16
	v_lshl_add_u64 v[38:39], v[34:35], 0, s[10:11]
	v_lshlrev_b64 v[38:39], 7, v[38:39]
	v_lshl_add_u64 v[48:49], v[36:37], 0, v[38:39]
	global_load_dwordx4 v[216:219], v[48:49], off
	global_load_dwordx4 v[220:223], v[48:49], off offset:16
	v_cmp_lt_i32_e32 vcc, v187, v186
	v_xor_b32_e32 v47, 2, v185
	v_readlane_b32 s4, v255, 8
	v_cndmask_b32_e32 v0, v185, v187, vcc
	v_lshlrev_b32_e32 v0, 2, v0
	v_cmp_lt_i32_e32 vcc, v47, v186
	v_lshl_add_u32 v50, v34, 3, s4
	s_nop 1
	v_cndmask_b32_e32 v47, v185, v47, vcc
	v_lshlrev_b32_e32 v48, 2, v47
	v_mov_b32_e32 v47, v50
	v_cmp_eq_u32_e32 vcc, 0, v45
	s_waitcnt vmcnt(7)
	v_pk_add_f32 v[224:225], v[192:193], v[194:195]
	s_waitcnt vmcnt(6)
	v_pk_add_f32 v[232:233], v[196:197], v[198:199]
	s_nop 0
	v_pk_add_f32 v[224:225], v[224:225], v[232:233]
	s_nop 0
	ds_bpermute_b32 v232, v0, v224
	ds_bpermute_b32 v233, v0, v225
	s_waitcnt vmcnt(5)
	v_pk_add_f32 v[226:227], v[200:201], v[202:203]
	s_waitcnt vmcnt(4)
	v_pk_add_f32 v[234:235], v[204:205], v[206:207]
	s_nop 0
	v_pk_add_f32 v[226:227], v[226:227], v[234:235]
	s_nop 0
	ds_bpermute_b32 v234, v0, v226
	ds_bpermute_b32 v235, v0, v227
	s_waitcnt vmcnt(3)
	v_pk_add_f32 v[228:229], v[208:209], v[210:211]
	s_waitcnt vmcnt(2)
	v_pk_add_f32 v[236:237], v[212:213], v[214:215]
	s_nop 0
	v_pk_add_f32 v[228:229], v[228:229], v[236:237]
	s_nop 0
	ds_bpermute_b32 v236, v0, v228
	ds_bpermute_b32 v237, v0, v229
	s_waitcnt vmcnt(1)
	v_pk_add_f32 v[230:231], v[216:217], v[218:219]
	s_waitcnt vmcnt(0)
	v_pk_add_f32 v[238:239], v[220:221], v[222:223]
	s_nop 0
	v_pk_add_f32 v[230:231], v[230:231], v[238:239]
	s_nop 0
	ds_bpermute_b32 v238, v0, v230
	ds_bpermute_b32 v239, v0, v231
	s_waitcnt lgkmcnt(6)
	v_pk_add_f32 v[224:225], v[224:225], v[232:233]
	s_nop 0
	ds_bpermute_b32 v232, v48, v224
	ds_bpermute_b32 v233, v48, v225
	s_waitcnt lgkmcnt(6)
	v_pk_add_f32 v[226:227], v[226:227], v[234:235]
	s_nop 0
	ds_bpermute_b32 v234, v48, v226
	ds_bpermute_b32 v235, v48, v227
	s_waitcnt lgkmcnt(6)
	v_pk_add_f32 v[228:229], v[228:229], v[236:237]
	s_nop 0
	ds_bpermute_b32 v236, v48, v228
	ds_bpermute_b32 v237, v48, v229
	s_waitcnt lgkmcnt(6)
	v_pk_add_f32 v[230:231], v[230:231], v[238:239]
	s_nop 0
	ds_bpermute_b32 v238, v48, v230
	ds_bpermute_b32 v239, v48, v231
	s_and_b64 exec, exec, vcc
	s_cbranch_execz .LBB0_478
	s_mov_b32 s4, 0x3a800000
	s_waitcnt lgkmcnt(6)
	v_pk_add_f32 v[224:225], v[224:225], v[232:233]
	s_nop 0
	v_pk_mul_f32 v[224:225], v[224:225], s[4:5] op_sel_hi:[1,0]
	s_nop 0
	v_fma_f32 v225, -v224, v224, v225
	v_add_f32_e32 v225, 0x358637bd, v225
	v_rsq_f32_e32 v225, v225
	s_nop 0
	ds_write_b64 v47, v[224:225]
	s_waitcnt lgkmcnt(4)
	v_pk_add_f32 v[226:227], v[226:227], v[234:235]
	s_nop 0
	v_pk_mul_f32 v[226:227], v[226:227], s[4:5] op_sel_hi:[1,0]
	s_nop 0
	v_fma_f32 v227, -v226, v226, v227
	v_add_f32_e32 v227, 0x358637bd, v227
	v_rsq_f32_e32 v227, v227
	s_nop 0
	ds_write_b64 v47, v[226:227] offset:1024
	s_waitcnt lgkmcnt(2)
	v_pk_add_f32 v[228:229], v[228:229], v[236:237]
	s_nop 0
	v_pk_mul_f32 v[228:229], v[228:229], s[4:5] op_sel_hi:[1,0]
	s_nop 0
	v_fma_f32 v229, -v228, v228, v229
	v_add_f32_e32 v229, 0x358637bd, v229
	v_rsq_f32_e32 v229, v229
	s_nop 0
	ds_write_b64 v47, v[228:229] offset:2048
	s_waitcnt lgkmcnt(0)
	v_pk_add_f32 v[230:231], v[230:231], v[238:239]
	s_nop 0
	v_pk_mul_f32 v[230:231], v[230:231], s[4:5] op_sel_hi:[1,0]
	s_nop 0
	v_fma_f32 v231, -v230, v230, v231
	v_add_f32_e32 v231, 0x358637bd, v231
	v_rsq_f32_e32 v231, v231
	s_nop 0
	ds_write_b64 v47, v[230:231] offset:3072
.LBB0_478:
	s_or_b64 exec, exec, s[16:17]
	s_lshl_b64 s[16:17], s[0:1], 2
	s_add_u32 s18, s25, s16
	s_addc_u32 s19, s26, s17
	s_add_u32 s16, s23, s16
	s_addc_u32 s17, s24, s17
	v_lshlrev_b32_e32 v0, 2, v46
	v_and_b32_e32 v39, -8, v44
	s_waitcnt lgkmcnt(0)
	v_lshl_add_u64 v[36:37], s[18:19], 0, v[0:1]
	v_lshl_add_u64 v[34:35], s[16:17], 0, v[0:1]
	global_load_dwordx4 v[192:195], v[36:37], off offset:16
	global_load_dwordx4 v[196:199], v[36:37], off
	global_load_dwordx4 v[200:203], v[34:35], off offset:16
	global_load_dwordx4 v[204:207], v[34:35], off
	v_lshl_add_u32 v0, v46, 1, 0
	v_lshrrev_b32_e32 v38, 3, v44
	v_add_u32_e32 v39, 0, v39
	s_barrier
	s_and_saveexec_b64 s[16:17], s[42:43]
	s_cbranch_execz .LBB0_480
	v_add_u32_e32 v40, 0x1a800, v39
	ds_read_b64 v[40:41], v40
	s_waitcnt vmcnt(4)
	v_lshlrev_b32_e32 v44, 16, v30
	v_and_b32_e32 v62, 0xffff0000, v30
	v_lshlrev_b32_e32 v30, 16, v31
	v_and_b32_e32 v31, 0xffff0000, v31
	v_lshlrev_b32_e32 v63, 16, v32
	v_and_b32_e32 v64, 0xffff0000, v32
	v_lshlrev_b32_e32 v65, 16, v33
	v_and_b32_e32 v66, 0xffff0000, v33
	s_waitcnt lgkmcnt(0)
	v_sub_f32_e32 v31, v31, v40
	v_sub_f32_e32 v30, v30, v40
	v_sub_f32_e32 v33, v62, v40
	v_sub_f32_e32 v32, v44, v40
	v_pk_mul_f32 v[32:33], v[40:41], v[32:33] op_sel:[1,0]
	v_pk_mul_f32 v[30:31], v[40:41], v[30:31] op_sel:[1,0]
	s_waitcnt vmcnt(0)
	v_pk_fma_f32 v[52:53], v[198:199], v[30:31], v[206:207]
	v_pk_fma_f32 v[30:31], v[196:197], v[32:33], v[204:205]
	v_sub_f32_e32 v33, v66, v40
	v_sub_f32_e32 v32, v65, v40
	v_sub_f32_e32 v51, v64, v40
	v_sub_f32_e32 v50, v63, v40
	v_pk_mul_f32 v[50:51], v[40:41], v[50:51] op_sel:[1,0]
	v_pk_mul_f32 v[32:33], v[40:41], v[32:33] op_sel:[1,0]
	v_cvt_pk_bf16_f32 v30, v30, v31
	v_pk_fma_f32 v[40:41], v[194:195], v[32:33], v[202:203]
	v_pk_fma_f32 v[32:33], v[192:193], v[50:51], v[200:201]
	v_cvt_pk_bf16_f32 v31, v52, v53
	v_cvt_pk_bf16_f32 v32, v32, v33
	v_cvt_pk_bf16_f32 v33, v40, v41
	v_mad_u64_u32 v[40:41], s[18:19], v38, s89, v[0:1]
	ds_write_b128 v40, v[30:33]

; #define LAS __attribute__((address_space(3)))
; __device__ __forceinline__ u32x4 pack8(f32x4 a, f32x4 b) { u32x4 w; w.x = pk2(a[0], a[1]); w.y = pk2(a[2], a[3]); w.z = pk2(b[0], b[1]); w.w = pk2(b[2], b[3]); return w; }
; __device__ __forceinline__ void gmlp_task(LAS unsigned char* lds, const Params& p, const bf16_t* P, bf16_t* Y, const float* svg, float* ssb, int l, bool sample, int b, int g, int q, int tid, int wave, int lane, bool load_ws = true) {
;     ...
;             const f32x4 g0 = *(const f32x4*)(lg + ch * 8), g1 = *(const f32x4*)(lg + ch * 8 + 4), b0 = *(const f32x4*)(lb + ch * 8), b1 = *(const f32x4*)(lb + ch * 8 + 4);
;             f32x4 v0 = (f32x4){bf_lo(w.x), bf_hi(w.x), bf_lo(w.y), bf_hi(w.y)}, v1 = (f32x4){bf_lo(w.z), bf_hi(w.z), bf_lo(w.w), bf_hi(w.w)};
;             v0 = (v0 - mean) * rstd * g0 + b0; v1 = (v1 - mean) * rstd * g1 + b1;
;             if (sample) { float* dst = p.out + OUT_VGS + ((((size_t)l * 32 + cidx) * 32 + j) * 16 + g) * 64 + ch * 8; *(f32x4*)dst = v0; *(f32x4*)(dst + 4) = v1; }
;             *(LAS u32x4*)(VGT + j * 72 + ch * 8) = pack8(v0, v1);
;     ...
;         const int i = 32 * it + r;
;         const float bias = p.b_spatial[(l * 16 + g) * 128 + i];
;         const int nks = 2 * (it + 1);
; #pragma unroll
;         for (int sub = 0; sub < 4; ++sub) {
;             const int cidx = q * 4 + sub;
;             const size_t row0 = sample ? (size_t)NP + cidx * 32 : (size_t)b * 2048 + cidx * 128;
;             const LAS bf16_t* VGT = (const LAS bf16_t*)(lds + vgt_off(sub));
;             const size_t row = row0 + i;
;             const bf16_t* up = P + row * DPROJ + O_U + g * 64 + 32 * dt + 8 * h;
;             const bf16_t* gp = P + row * DPROJ + O_GB + g * 64 + 32 * dt + 8 * h;
;             u32x4 uw[2], gw[2];
; #pragma unroll
;             for (int pr = 0; pr < 2; ++pr) { uw[pr] = *(const u32x4*)(up + 16 * pr); gw[pr] = *(const u32x4*)(gp + 16 * pr); }
;             f32x16 acc;
; #pragma unroll
;             for (int e = 0; e < 16; ++e) acc[e] = 0.f;
;             const LAS bf16_t* tr = VGT + (8 * h + ((lane & 15) >> 2)) * 72 + 32 * dt + 16 * ((lane >> 4) & 1) + 4 * (lane & 3);
.LBB0_487:
	v_add_u32_e32 v6, 0x1b400, v31
	ds_read_b64 v[22:23], v6
	v_lshlrev_b32_e32 v24, 16, v2
	v_and_b32_e32 v25, 0xffff0000, v2
	v_lshlrev_b32_e32 v2, 16, v3
	v_and_b32_e32 v3, 0xffff0000, v3
	v_lshlrev_b32_e32 v26, 16, v4
	v_and_b32_e32 v27, 0xffff0000, v4
	v_lshlrev_b32_e32 v28, 16, v5
	v_and_b32_e32 v29, 0xffff0000, v5
	s_waitcnt lgkmcnt(0)
	v_sub_f32_e32 v3, v3, v22
	v_sub_f32_e32 v2, v2, v22
	v_sub_f32_e32 v5, v25, v22
	v_sub_f32_e32 v4, v24, v22
	v_pk_mul_f32 v[4:5], v[22:23], v[4:5] op_sel:[1,0]
	v_pk_mul_f32 v[2:3], v[22:23], v[2:3] op_sel:[1,0]
	s_waitcnt vmcnt(0)
	v_pk_fma_f32 v[12:13], v[198:199], v[2:3], v[206:207]
	v_pk_fma_f32 v[2:3], v[196:197], v[4:5], v[204:205]
	v_sub_f32_e32 v5, v29, v22
	v_sub_f32_e32 v4, v28, v22
	v_sub_f32_e32 v11, v27, v22
	v_sub_f32_e32 v10, v26, v22
	v_pk_mul_f32 v[10:11], v[22:23], v[10:11] op_sel:[1,0]
	v_pk_mul_f32 v[4:5], v[22:23], v[4:5] op_sel:[1,0]
	v_cvt_pk_bf16_f32 v2, v2, v3
	v_pk_fma_f32 v[8:9], v[194:195], v[4:5], v[202:203]
	v_pk_fma_f32 v[4:5], v[192:193], v[10:11], v[200:201]
	v_cvt_pk_bf16_f32 v3, v12, v13
	v_cvt_pk_bf16_f32 v4, v4, v5
	v_cvt_pk_bf16_f32 v5, v8, v9
	v_mad_u64_u32 v[6:7], s[18:19], v30, s89, v[0:1]
	ds_write_b128 v6, v[2:5] offset:55296
.LBB0_488:
	s_or_b64 exec, exec, s[16:17]
	v_and_b32_e32 v10, 31, v42
	v_readlane_b32 s4, v253, 39
	s_lshl_b32 s11, s33, 7
	s_add_i32 s11, s11, s22
	v_or_b32_e32 v38, s4, v10
	v_add_u32_e32 v2, s11, v38
	v_ashrrev_i32_e32 v3, 31, v2
	v_lshl_add_u64 v[2:3], v[2:3], 2, s[64:65]
	s_waitcnt lgkmcnt(0)
	s_barrier
	global_load_dword v36, v[2:3], off
	v_add_u32_e32 v0, s44, v38
	v_mov_b64_e32 v[2:3], s[68:69]
	v_ashrrev_i32_e32 v11, 2, v42
	v_mad_u64_u32 v[2:3], s[16:17], v0, s73, v[2:3]
	v_readlane_b32 s4, v253, 40
	v_and_b32_e32 v34, -8, v11
	s_lshl_b32 s44, s4, 1
	v_lshl_add_u64 v[2:3], s[0:1], 1, v[2:3]
	v_ashrrev_i32_e32 v35, 31, v34
	v_lshl_add_u64 v[2:3], v[2:3], 0, s[44:45]
	v_lshl_add_u64 v[2:3], v[34:35], 1, v[2:3]
	s_mov_b64 s[4:5], 0x1400
	v_lshl_add_u64 v[4:5], v[2:3], 0, s[4:5]
	s_mov_b64 s[4:5], 0x2400
	v_lshl_add_u64 v[6:7], v[2:3], 0, s[4:5]
	s_movk_i32 s4, 0x1000
	v_add_co_u32_e32 v8, vcc, s4, v2
	s_movk_i32 s4, 0x2000
	s_nop 0
	v_addc_co_u32_e32 v9, vcc, 0, v3, vcc
	v_add_co_u32_e32 v2, vcc, s4, v2
	v_readlane_b32 s4, v254, 55
	s_nop 0
	v_addc_co_u32_e32 v3, vcc, 0, v3, vcc
	global_load_dwordx4 v[30:33], v[8:9], off offset:1024
	global_load_dwordx4 v[26:29], v[2:3], off offset:1024
	global_load_dwordx4 v[22:25], v[4:5], off offset:32
	global_load_dwordx4 v[18:21], v[6:7], off offset:32
	v_add_u32_e32 v132, s14, v38
	v_mov_b64_e32 v[134:135], s[68:69]
	v_mad_u64_u32 v[134:135], vcc, v132, s73, v[134:135]
	v_lshl_add_u64 v[134:135], s[0:1], 1, v[134:135]
	v_lshl_add_u64 v[134:135], v[134:135], 0, s[44:45]
	v_lshl_add_u64 v[134:135], v[34:35], 1, v[134:135]
	s_mov_b64 s[16:17], 0x1000
	v_lshl_add_u64 v[136:137], v[134:135], 0, s[16:17]
	s_mov_b64 s[16:17], 0x2000
	v_lshl_add_u64 v[138:139], v[134:135], 0, s[16:17]
	s_mov_b64 s[16:17], 0x1400
	v_lshl_add_u64 v[140:141], v[134:135], 0, s[16:17]
	s_mov_b64 s[16:17], 0x2400
	v_lshl_add_u64 v[142:143], v[134:135], 0, s[16:17]
	global_load_dwordx4 v[80:83], v[136:137], off offset:1024
	global_load_dwordx4 v[76:79], v[138:139], off offset:1024
	global_load_dwordx4 v[72:75], v[140:141], off offset:32
	global_load_dwordx4 v[68:71], v[142:143], off offset:32
	v_add_u32_e32 v132, s12, v38
	v_mov_b64_e32 v[134:135], s[68:69]
	v_mad_u64_u32 v[134:135], vcc, v132, s73, v[134:135]
	v_lshl_add_u64 v[134:135], s[0:1], 1, v[134:135]
	v_lshl_add_u64 v[134:135], v[134:135], 0, s[44:45]
	v_lshl_add_u64 v[134:135], v[34:35], 1, v[134:135]
	s_mov_b64 s[16:17], 0x1000
	v_lshl_add_u64 v[136:137], v[134:135], 0, s[16:17]
	s_mov_b64 s[16:17], 0x2000
	v_lshl_add_u64 v[138:139], v[134:135], 0, s[16:17]
	s_mov_b64 s[16:17], 0x1400
	v_lshl_add_u64 v[140:141], v[134:135], 0, s[16:17]
	s_mov_b64 s[16:17], 0x2400
	v_lshl_add_u64 v[142:143], v[134:135], 0, s[16:17]
	global_load_dwordx4 v[96:99], v[136:137], off offset:1024
	global_load_dwordx4 v[92:95], v[138:139], off offset:1024
	global_load_dwordx4 v[88:91], v[140:141], off offset:32
	global_load_dwordx4 v[84:87], v[142:143], off offset:32
	v_add_u32_e32 v132, s10, v38
	v_mov_b64_e32 v[134:135], s[68:69]
	v_mad_u64_u32 v[134:135], vcc, v132, s73, v[134:135]
	v_lshl_add_u64 v[134:135], s[0:1], 1, v[134:135]
	v_lshl_add_u64 v[134:135], v[134:135], 0, s[44:45]
	v_lshl_add_u64 v[134:135], v[34:35], 1, v[134:135]
	s_mov_b64 s[16:17], 0x1000
	v_lshl_add_u64 v[136:137], v[134:135], 0, s[16:17]
	s_mov_b64 s[16:17], 0x2000
	v_lshl_add_u64 v[138:139], v[134:135], 0, s[16:17]
	s_mov_b64 s[16:17], 0x1400
	v_lshl_add_u64 v[140:141], v[134:135], 0, s[16:17]
	s_mov_b64 s[16:17], 0x2400
	v_lshl_add_u64 v[142:143], v[134:135], 0, s[16:17]
	global_load_dwordx4 v[112:115], v[136:137], off offset:1024
	global_load_dwordx4 v[108:111], v[138:139], off offset:1024
	global_load_dwordx4 v[104:107], v[140:141], off offset:32
	global_load_dwordx4 v[100:103], v[142:143], off offset:32
	v_lshrrev_b32_e32 v4, 3, v11
	v_mul_u32_u24_e32 v3, 0x110, v10
	v_lshlrev_b32_e32 v5, 4, v4
	s_movk_i32 s11, 0x480
	v_bfe_u32 v2, v42, 2, 2
	v_add3_u32 v37, v3, v5, s4
	v_mul_lo_u32 v3, v4, s11
	v_mad_u32_u24 v2, v2, s89, v3
	v_lshlrev_b32_e32 v3, 1, v42
	v_and_b32_e32 v3, 32, v3
	v_lshlrev_b32_e32 v4, 3, v45
	v_add3_u32 v39, v2, v3, v4
	v_readlane_b32 s4, v254, 58
	v_mov_b32_e32 v2, 0
	v_mov_b32_e32 v41, v37
	v_add_u32_e32 v40, s4, v39
	s_mov_b32 s11, s77
	v_mov_b32_e32 v3, v2
	v_mov_b32_e32 v4, v2
	v_mov_b32_e32 v5, v2
	v_mov_b32_e32 v6, v2
	v_mov_b32_e32 v7, v2
	v_mov_b32_e32 v8, v2
	v_mov_b32_e32 v9, v2
	v_mov_b32_e32 v10, v2
	v_mov_b32_e32 v11, v2
	v_mov_b32_e32 v12, v2
	v_mov_b32_e32 v13, v2
	v_mov_b32_e32 v14, v2
	v_mov_b32_e32 v15, v2
	v_mov_b32_e32 v16, v2
	v_mov_b32_e32 v17, v2
; #define LAS __attribute__((address_space(3)))
; __device__ __forceinline__ unsigned pk2(float lo, float hi) { const f32x2 v = {lo, hi}; return __builtin_bit_cast(unsigned, __builtin_convertvector(v, bf16x2_t)); }
; #define MFMA32(a, b, c) __builtin_amdgcn_mfma_f32_32x32x16_bf16((a), (b), (c), 0, 0, 0)
; __device__ __forceinline__ void gmlp_task(LAS unsigned char* lds, const Params& p, const bf16_t* P, bf16_t* Y, const float* svg, float* ssb, int l, bool sample, int b, int g, int q, int tid, int wave, int lane, bool load_ws = true) {
;     ...
;             for (int ks = 0; ks < nks; ++ks) {
;                 const s16x4 alo = __builtin_amdgcn_ds_read_tr16_b64_v4i16((LAS s16x4*)(tr + 16 * ks * 72)), ahi = __builtin_amdgcn_ds_read_tr16_b64_v4i16((LAS s16x4*)(tr + (16 * ks + 4) * 72));
;                 const bf16x8 a = __builtin_shufflevector(alo, ahi, 0, 1, 2, 3, 4, 5, 6, 7);
;                 const bf16x8 bw = *(const LAS bf16x8*)(WSL + (32 * it + r) * 136 + 16 * ks + 8 * h);
;                 acc = MFMA32(a, bw, acc);
;             }
;             bf16_t* yp = Y + row * DM + 1024 + g * 64 + 32 * dt + 8 * h;
;             float ss = 0.f;
; #pragma unroll
;             for (int pr = 0; pr < 2; ++pr) {
;                 float a[4], bq[4];
; #pragma unroll
;                 for (int k = 0; k < 4; ++k) { a[k] = acc[8 * pr + k] + bias; bq[k] = acc[8 * pr + 4 + k] + bias; }
; #pragma unroll
;                 for (int k = 0; k < 4; ++k) swap_halves(a[k], bq[k]);
;                 const u32x4 u4 = uw[pr], g4 = gw[pr];
;                 a[0] *= bf_lo(u4.x); a[1] *= bf_hi(u4.x); a[2] *= bf_lo(u4.y); a[3] *= bf_hi(u4.y); bq[0] *= bf_lo(u4.z); bq[1] *= bf_hi(u4.z); bq[2] *= bf_lo(u4.w); bq[3] *= bf_hi(u4.w);
;                 ss += ((a[0] * a[0] + a[1] * a[1]) + (a[2] * a[2] + a[3] * a[3])) + ((bq[0] * bq[0] + bq[1] * bq[1]) + (bq[2] * bq[2] + bq[3] * bq[3]));
;                 u32x4 w; w.x = pk2(a[0] * bf_lo(g4.x), a[1] * bf_hi(g4.x)); w.y = pk2(a[2] * bf_lo(g4.y), a[3] * bf_hi(g4.y));
;                 w.z = pk2(bq[0] * bf_lo(g4.z), bq[1] * bf_hi(g4.z)); w.w = pk2(bq[2] * bf_lo(g4.w), bq[3] * bf_hi(g4.w));
;                 *(u32x4*)(yp + 16 * pr) = w;
;             }
;             ss += __shfl_xor(ss, 32);
;             if (h == 0) ssb[row * 32 + g * 2 + dt] = ss;
.LBB0_489:
	ds_read_b64_tr_b16 v[44:45], v40
	ds_read_b64_tr_b16 v[46:47], v40 offset:576
	ds_read_b128 v[48:51], v41
	s_add_i32 s11, s11, -1
	v_add_u32_e32 v41, 32, v41
	s_cmp_eq_u32 s11, 0
	v_add_u32_e32 v40, 0x900, v40
	s_waitcnt lgkmcnt(0)
	v_mfma_f32_32x32x16_bf16 v[2:17], v[44:47], v[48:51], v[2:17]
	s_cbranch_scc0 .LBB0_489
	v_lshlrev_b64 v[40:41], 12, v[0:1]
	v_lshl_add_u64 v[40:41], s[36:37], 0, v[40:41]
	v_lshl_add_u64 v[40:41], s[0:1], 1, v[40:41]
	s_waitcnt vmcnt(16)
	s_nop 6
	v_add_f32_e32 v2, v36, v2
	v_add_f32_e32 v6, v36, v6
	v_add_f32_e32 v3, v36, v3
	v_add_f32_e32 v7, v36, v7
	v_add_f32_e32 v4, v36, v4
	v_add_f32_e32 v8, v36, v8
	v_add_f32_e32 v5, v36, v5
	v_add_f32_e32 v9, v36, v9
	v_lshl_add_u64 v[40:41], v[40:41], 0, s[44:45]
	v_permlane32_swap_b32_e32 v2, v6
	v_permlane32_swap_b32_e32 v3, v7
	v_permlane32_swap_b32_e32 v4, v8
	v_permlane32_swap_b32_e32 v5, v9
	v_cmp_gt_u32_e64 s[40:41], 32, v42
	v_lshl_add_u64 v[42:43], v[34:35], 1, v[40:41]
	s_waitcnt vmcnt(15)
	v_lshlrev_b32_e32 v40, 16, v30
	v_and_b32_e32 v41, 0xffff0000, v30
	v_lshlrev_b32_e32 v30, 16, v31
	v_and_b32_e32 v31, 0xffff0000, v31
	v_pk_mul_f32 v[2:3], v[40:41], v[2:3]
	s_waitcnt vmcnt(14)
	v_lshlrev_b32_e32 v44, 16, v26
	v_and_b32_e32 v45, 0xffff0000, v26
	v_pk_mul_f32 v[4:5], v[30:31], v[4:5]
	v_lshlrev_b32_e32 v26, 16, v27
	v_and_b32_e32 v27, 0xffff0000, v27
	v_pk_mul_f32 v[40:41], v[2:3], v[2:3]
	v_pk_mul_f32 v[2:3], v[2:3], v[44:45]
	v_pk_mul_f32 v[30:31], v[4:5], v[4:5]
	v_pk_mul_f32 v[4:5], v[4:5], v[26:27]
	v_cvt_pk_bf16_f32 v2, v2, v3
	v_cvt_pk_bf16_f32 v3, v4, v5
	v_lshlrev_b32_e32 v4, 16, v32
	v_and_b32_e32 v5, 0xffff0000, v32
	v_pk_mul_f32 v[4:5], v[4:5], v[6:7]
	v_lshlrev_b32_e32 v6, 16, v28
	v_and_b32_e32 v7, 0xffff0000, v28
	v_pk_mul_f32 v[26:27], v[4:5], v[4:5]
	v_pk_mul_f32 v[4:5], v[4:5], v[6:7]
	v_lshlrev_b32_e32 v6, 16, v33
	v_and_b32_e32 v7, 0xffff0000, v33
	v_pk_mul_f32 v[6:7], v[6:7], v[8:9]
	v_lshlrev_b32_e32 v28, 16, v29
	v_and_b32_e32 v29, 0xffff0000, v29
	v_pk_mul_f32 v[8:9], v[6:7], v[6:7]
	v_pk_mul_f32 v[6:7], v[6:7], v[28:29]
	v_cvt_pk_bf16_f32 v4, v4, v5
	v_cvt_pk_bf16_f32 v5, v6, v7
	global_store_dwordx4 v[42:43], v[2:5], off offset:2048
	v_add_f32_e32 v6, v36, v14
	v_add_f32_e32 v7, v36, v15
	v_add_f32_e32 v2, v36, v10
	v_add_f32_e32 v3, v36, v11
	s_nop 0
	v_permlane32_swap_b32_e32 v2, v6
	v_permlane32_swap_b32_e32 v3, v7
	s_waitcnt vmcnt(14)
	v_lshlrev_b32_e32 v4, 16, v22
	v_and_b32_e32 v5, 0xffff0000, v22
	v_pk_mul_f32 v[2:3], v[4:5], v[2:3]
	s_waitcnt vmcnt(13)
	v_lshlrev_b32_e32 v4, 16, v18
	v_and_b32_e32 v5, 0xffff0000, v18
	v_add_f32_e32 v10, v36, v12
	v_add_f32_e32 v12, v36, v16
	v_add_f32_e32 v11, v36, v13
	v_add_f32_e32 v13, v36, v17
	v_pk_mul_f32 v[14:15], v[2:3], v[2:3]
	v_pk_mul_f32 v[2:3], v[2:3], v[4:5]
	v_permlane32_swap_b32_e32 v10, v12
	v_permlane32_swap_b32_e32 v11, v13
	v_cvt_pk_bf16_f32 v4, v2, v3
	v_lshlrev_b32_e32 v2, 16, v23
	v_and_b32_e32 v3, 0xffff0000, v23
	v_lshlrev_b32_e32 v16, 16, v19
	v_pk_mul_f32 v[2:3], v[2:3], v[10:11]
	v_and_b32_e32 v17, 0xffff0000, v19
	v_pk_mul_f32 v[10:11], v[2:3], v[2:3]
	v_pk_mul_f32 v[2:3], v[2:3], v[16:17]
	s_lshl_b32 s16, s33, 1
	v_cvt_pk_bf16_f32 v5, v2, v3
	v_lshlrev_b32_e32 v2, 16, v24
	v_and_b32_e32 v3, 0xffff0000, v24
	v_pk_mul_f32 v[2:3], v[2:3], v[6:7]
	v_lshlrev_b32_e32 v6, 16, v20
	v_and_b32_e32 v7, 0xffff0000, v20
	v_pk_mul_f32 v[16:17], v[2:3], v[2:3]
	v_pk_mul_f32 v[2:3], v[2:3], v[6:7]
	v_add_f32_e32 v7, v8, v9
	v_cvt_pk_bf16_f32 v6, v2, v3
	v_lshlrev_b32_e32 v2, 16, v25
	v_and_b32_e32 v3, 0xffff0000, v25
	v_pk_mul_f32 v[12:13], v[2:3], v[12:13]
	v_add_f32_e32 v8, v26, v27
	v_pk_mul_f32 v[2:3], v[12:13], v[12:13]
	v_add_f32_e32 v7, v8, v7
	v_add_f32_e32 v8, v30, v31
	v_add_f32_e32 v9, v40, v41
	v_add_f32_e32 v8, v9, v8
	v_add_f32_e32 v2, v2, v3
	v_add_f32_e32 v3, v16, v17
	v_add_f32_e32 v7, v8, v7
	v_add_f32_e32 v2, v3, v2
	v_add_f32_e32 v3, v10, v11
	v_add_f32_e32 v8, v14, v15
	v_add_f32_e32 v3, v8, v3
	v_add_f32_e32 v2, v3, v2
	v_xor_b32_e32 v3, 32, v185
	v_cmp_lt_i32_e32 vcc, v3, v186
	v_add_f32_e32 v2, v7, v2
	s_ashr_i32 s17, s16, 31
	v_cndmask_b32_e32 v3, v185, v3, vcc
	v_lshlrev_b32_e32 v40, 2, v3
	ds_bpermute_b32 v3, v40, v2
	s_lshl_b64 s[16:17], s[16:17], 2
	v_readlane_b32 s4, v253, 41
	v_lshlrev_b32_e32 v8, 16, v21
	v_and_b32_e32 v9, 0xffff0000, v21
	s_add_u32 s16, s4, s16
	v_readlane_b32 s4, v253, 44
	v_pk_mul_f32 v[8:9], v[12:13], v[8:9]
	s_addc_u32 s17, s4, s17
	v_cvt_pk_bf16_f32 v7, v8, v9
	global_store_dwordx4 v[42:43], v[4:7], off offset:2080
	s_and_saveexec_b64 s[18:19], s[40:41]
	s_cbranch_execz .LBB0_492
	v_lshlrev_b64 v[4:5], 7, v[0:1]
	v_lshl_add_u64 v[4:5], s[16:17], 0, v[4:5]
	s_waitcnt lgkmcnt(0)
	v_add_f32_e32 v0, v2, v3
	global_store_dword v[4:5], v0, off
.LBB0_492:
	s_or_b64 exec, exec, s[18:19]
	v_add_u32_e32 v0, s14, v38
	s_waitcnt lgkmcnt(0)
	v_mov_b64_e32 v[2:3], s[68:69]
	v_mad_u64_u32 v[2:3], s[14:15], v0, s73, v[2:3]
	v_lshl_add_u64 v[2:3], s[0:1], 1, v[2:3]
	v_lshl_add_u64 v[2:3], v[2:3], 0, s[44:45]
	v_lshl_add_u64 v[2:3], v[34:35], 1, v[2:3]
	s_mov_b64 s[4:5], 0x1400
	v_add_co_u32_e32 v8, vcc, 0x1000, v2
	v_lshl_add_u64 v[4:5], v[2:3], 0, s[4:5]
	s_mov_b64 s[4:5], 0x2400
	v_addc_co_u32_e32 v9, vcc, 0, v3, vcc
	v_lshl_add_u64 v[6:7], v[2:3], 0, s[4:5]
	v_add_co_u32_e32 v2, vcc, 0x2000, v2
	v_readlane_b32 s4, v254, 56
	s_nop 0
	v_addc_co_u32_e32 v3, vcc, 0, v3, vcc
	v_mov_b32_e32 v2, 0
	v_add_u32_e32 v41, s4, v39
	v_mov_b32_e32 v42, v37
	s_mov_b32 s11, s77
	v_mov_b32_e32 v3, v2
	v_mov_b32_e32 v4, v2
	v_mov_b32_e32 v5, v2
	v_mov_b32_e32 v6, v2
	v_mov_b32_e32 v7, v2
	v_mov_b32_e32 v8, v2
	v_mov_b32_e32 v9, v2
	v_mov_b32_e32 v10, v2
	v_mov_b32_e32 v11, v2
	v_mov_b32_e32 v12, v2
	v_mov_b32_e32 v13, v2
	v_mov_b32_e32 v14, v2
	v_mov_b32_e32 v15, v2
	v_mov_b32_e32 v16, v2
	v_mov_b32_e32 v17, v2
; #define LAS __attribute__((address_space(3)))
; __device__ __forceinline__ unsigned pk2(float lo, float hi) { const f32x2 v = {lo, hi}; return __builtin_bit_cast(unsigned, __builtin_convertvector(v, bf16x2_t)); }
; #define MFMA32(a, b, c) __builtin_amdgcn_mfma_f32_32x32x16_bf16((a), (b), (c), 0, 0, 0)
; __device__ __forceinline__ void gmlp_task(LAS unsigned char* lds, const Params& p, const bf16_t* P, bf16_t* Y, const float* svg, float* ssb, int l, bool sample, int b, int g, int q, int tid, int wave, int lane, bool load_ws = true) {
;     ...
;             for (int ks = 0; ks < nks; ++ks) {
;                 const s16x4 alo = __builtin_amdgcn_ds_read_tr16_b64_v4i16((LAS s16x4*)(tr + 16 * ks * 72)), ahi = __builtin_amdgcn_ds_read_tr16_b64_v4i16((LAS s16x4*)(tr + (16 * ks + 4) * 72));
;                 const bf16x8 a = __builtin_shufflevector(alo, ahi, 0, 1, 2, 3, 4, 5, 6, 7);
;                 const bf16x8 bw = *(const LAS bf16x8*)(WSL + (32 * it + r) * 136 + 16 * ks + 8 * h);
;                 acc = MFMA32(a, bw, acc);
;             }
;             bf16_t* yp = Y + row * DM + 1024 + g * 64 + 32 * dt + 8 * h;
;             float ss = 0.f;
; #pragma unroll
;             for (int pr = 0; pr < 2; ++pr) {
;                 float a[4], bq[4];
; #pragma unroll
;                 for (int k = 0; k < 4; ++k) { a[k] = acc[8 * pr + k] + bias; bq[k] = acc[8 * pr + 4 + k] + bias; }
; #pragma unroll
;                 for (int k = 0; k < 4; ++k) swap_halves(a[k], bq[k]);
;                 const u32x4 u4 = uw[pr], g4 = gw[pr];
;                 a[0] *= bf_lo(u4.x); a[1] *= bf_hi(u4.x); a[2] *= bf_lo(u4.y); a[3] *= bf_hi(u4.y); bq[0] *= bf_lo(u4.z); bq[1] *= bf_hi(u4.z); bq[2] *= bf_lo(u4.w); bq[3] *= bf_hi(u4.w);
;                 ss += ((a[0] * a[0] + a[1] * a[1]) + (a[2] * a[2] + a[3] * a[3])) + ((bq[0] * bq[0] + bq[1] * bq[1]) + (bq[2] * bq[2] + bq[3] * bq[3]));
;                 u32x4 w; w.x = pk2(a[0] * bf_lo(g4.x), a[1] * bf_hi(g4.x)); w.y = pk2(a[2] * bf_lo(g4.y), a[3] * bf_hi(g4.y));
;                 w.z = pk2(bq[0] * bf_lo(g4.z), bq[1] * bf_hi(g4.z)); w.w = pk2(bq[2] * bf_lo(g4.w), bq[3] * bf_hi(g4.w));
;                 *(u32x4*)(yp + 16 * pr) = w;
;             }
;             ss += __shfl_xor(ss, 32);
;             if (h == 0) ssb[row * 32 + g * 2 + dt] = ss;
.LBB0_493:
	v_add_u32_e32 v43, 0xfffffdc0, v41
	ds_read_b64_tr_b16 v[44:45], v43
	ds_read_b64_tr_b16 v[46:47], v41
	ds_read_b128 v[48:51], v42
	s_add_i32 s11, s11, -1
	v_add_u32_e32 v42, 32, v42
	s_cmp_lg_u32 s11, 0
	v_add_u32_e32 v41, 0x900, v41
	s_waitcnt lgkmcnt(0)
	v_mfma_f32_32x32x16_bf16 v[2:17], v[44:47], v[48:51], v[2:17]
	s_cbranch_scc1 .LBB0_493
	s_nop 10
	v_add_f32_e32 v2, v36, v2
	v_add_f32_e32 v6, v36, v6
	v_add_f32_e32 v3, v36, v3
	v_add_f32_e32 v7, v36, v7
	v_add_f32_e32 v4, v36, v4
	v_add_f32_e32 v8, v36, v8
	v_add_f32_e32 v5, v36, v5
	v_add_f32_e32 v9, v36, v9
	v_permlane32_swap_b32_e32 v2, v6
	v_permlane32_swap_b32_e32 v3, v7
	v_permlane32_swap_b32_e32 v4, v8
	v_permlane32_swap_b32_e32 v5, v9
	s_waitcnt vmcnt(14)
	v_lshlrev_b32_e32 v44, 16, v80
	v_and_b32_e32 v45, 0xffff0000, v80
	v_lshlrev_b32_e32 v30, 16, v81
	v_and_b32_e32 v31, 0xffff0000, v81
	v_pk_mul_f32 v[2:3], v[44:45], v[2:3]
	s_waitcnt vmcnt(13)
	v_lshlrev_b32_e32 v46, 16, v76
	v_and_b32_e32 v47, 0xffff0000, v76
	v_pk_mul_f32 v[4:5], v[30:31], v[4:5]
	v_lshlrev_b32_e32 v26, 16, v77
	v_and_b32_e32 v27, 0xffff0000, v77
	v_pk_mul_f32 v[44:45], v[2:3], v[2:3]
	v_pk_mul_f32 v[2:3], v[2:3], v[46:47]
	v_pk_mul_f32 v[30:31], v[4:5], v[4:5]
	v_pk_mul_f32 v[4:5], v[4:5], v[26:27]
	v_cvt_pk_bf16_f32 v2, v2, v3
	v_cvt_pk_bf16_f32 v3, v4, v5
	v_lshlrev_b32_e32 v4, 16, v82
	v_and_b32_e32 v5, 0xffff0000, v82
	v_lshlrev_b64 v[42:43], 12, v[0:1]
	v_pk_mul_f32 v[4:5], v[4:5], v[6:7]
	v_lshlrev_b32_e32 v6, 16, v78
	v_and_b32_e32 v7, 0xffff0000, v78
	v_lshl_add_u64 v[42:43], s[36:37], 0, v[42:43]
	v_pk_mul_f32 v[26:27], v[4:5], v[4:5]
	v_pk_mul_f32 v[4:5], v[4:5], v[6:7]
	v_lshlrev_b32_e32 v6, 16, v83
	v_and_b32_e32 v7, 0xffff0000, v83
	v_lshl_add_u64 v[42:43], s[0:1], 1, v[42:43]
	v_pk_mul_f32 v[6:7], v[6:7], v[8:9]
	v_lshlrev_b32_e32 v28, 16, v79
	v_and_b32_e32 v29, 0xffff0000, v79
	v_lshl_add_u64 v[42:43], v[42:43], 0, s[44:45]
	v_pk_mul_f32 v[8:9], v[6:7], v[6:7]
	v_pk_mul_f32 v[6:7], v[6:7], v[28:29]
	v_lshl_add_u64 v[42:43], v[34:35], 1, v[42:43]
	v_cvt_pk_bf16_f32 v4, v4, v5
	v_cvt_pk_bf16_f32 v5, v6, v7
	global_store_dwordx4 v[42:43], v[2:5], off offset:2048
	v_add_f32_e32 v6, v36, v14
	v_add_f32_e32 v7, v36, v15
	v_add_f32_e32 v2, v36, v10
	v_add_f32_e32 v3, v36, v11
	s_nop 0
	v_permlane32_swap_b32_e32 v2, v6
	v_permlane32_swap_b32_e32 v3, v7
	s_waitcnt vmcnt(13)
	v_lshlrev_b32_e32 v4, 16, v72
	v_and_b32_e32 v5, 0xffff0000, v72
	v_pk_mul_f32 v[2:3], v[4:5], v[2:3]
	s_waitcnt vmcnt(12)
	v_lshlrev_b32_e32 v4, 16, v68
	v_and_b32_e32 v5, 0xffff0000, v68
	v_add_f32_e32 v10, v36, v12
	v_add_f32_e32 v12, v36, v16
	v_add_f32_e32 v11, v36, v13
	v_add_f32_e32 v13, v36, v17
	v_pk_mul_f32 v[14:15], v[2:3], v[2:3]
	v_pk_mul_f32 v[2:3], v[2:3], v[4:5]
	v_permlane32_swap_b32_e32 v10, v12
	v_permlane32_swap_b32_e32 v11, v13
	v_cvt_pk_bf16_f32 v4, v2, v3
	v_lshlrev_b32_e32 v2, 16, v73
	v_and_b32_e32 v3, 0xffff0000, v73
	v_lshlrev_b32_e32 v16, 16, v69
	v_pk_mul_f32 v[2:3], v[2:3], v[10:11]
	v_and_b32_e32 v17, 0xffff0000, v69
	v_pk_mul_f32 v[10:11], v[2:3], v[2:3]
	v_pk_mul_f32 v[2:3], v[2:3], v[16:17]
	s_nop 0
	v_cvt_pk_bf16_f32 v5, v2, v3
	v_lshlrev_b32_e32 v2, 16, v74
	v_and_b32_e32 v3, 0xffff0000, v74
	v_pk_mul_f32 v[2:3], v[2:3], v[6:7]
	v_lshlrev_b32_e32 v6, 16, v70
	v_and_b32_e32 v7, 0xffff0000, v70
	v_pk_mul_f32 v[16:17], v[2:3], v[2:3]
	v_pk_mul_f32 v[2:3], v[2:3], v[6:7]
	v_add_f32_e32 v7, v8, v9
	v_cvt_pk_bf16_f32 v6, v2, v3
	v_lshlrev_b32_e32 v2, 16, v75
	v_and_b32_e32 v3, 0xffff0000, v75
	v_pk_mul_f32 v[12:13], v[2:3], v[12:13]
	v_add_f32_e32 v8, v26, v27
	v_pk_mul_f32 v[2:3], v[12:13], v[12:13]
	v_add_f32_e32 v7, v8, v7
	v_add_f32_e32 v8, v30, v31
	v_add_f32_e32 v9, v44, v45
	v_add_f32_e32 v8, v9, v8
	v_add_f32_e32 v2, v2, v3
	v_add_f32_e32 v3, v16, v17
	v_add_f32_e32 v7, v8, v7
	v_add_f32_e32 v2, v3, v2
	v_add_f32_e32 v3, v10, v11
	v_add_f32_e32 v8, v14, v15
	v_add_f32_e32 v3, v8, v3
	v_add_f32_e32 v2, v3, v2
	v_add_f32_e32 v2, v7, v2
	ds_bpermute_b32 v3, v40, v2
	v_lshlrev_b32_e32 v8, 16, v71
	v_and_b32_e32 v9, 0xffff0000, v71
	v_pk_mul_f32 v[8:9], v[12:13], v[8:9]
	s_nop 0
	v_cvt_pk_bf16_f32 v7, v8, v9
	global_store_dwordx4 v[42:43], v[4:7], off offset:2080
	s_and_saveexec_b64 s[14:15], s[40:41]
	s_cbranch_execz .LBB0_496
	v_lshlrev_b64 v[4:5], 7, v[0:1]
	v_lshl_add_u64 v[4:5], s[16:17], 0, v[4:5]
	s_waitcnt lgkmcnt(0)
	v_add_f32_e32 v0, v2, v3
	global_store_dword v[4:5], v0, off
.LBB0_496:
	s_or_b64 exec, exec, s[14:15]
	v_add_u32_e32 v0, s12, v38
	s_waitcnt lgkmcnt(0)
	v_mov_b64_e32 v[2:3], s[68:69]
	v_mad_u64_u32 v[2:3], s[12:13], v0, s73, v[2:3]
	v_lshl_add_u64 v[2:3], s[0:1], 1, v[2:3]
	v_lshl_add_u64 v[2:3], v[2:3], 0, s[44:45]
	v_lshl_add_u64 v[2:3], v[34:35], 1, v[2:3]
	s_mov_b64 s[4:5], 0x1400
	v_add_co_u32_e32 v8, vcc, 0x1000, v2
	v_lshl_add_u64 v[4:5], v[2:3], 0, s[4:5]
	s_mov_b64 s[4:5], 0x2400
	v_addc_co_u32_e32 v9, vcc, 0, v3, vcc
	v_lshl_add_u64 v[6:7], v[2:3], 0, s[4:5]
	v_add_co_u32_e32 v2, vcc, 0x2000, v2
	v_readlane_b32 s4, v254, 57
	s_nop 0
	v_addc_co_u32_e32 v3, vcc, 0, v3, vcc
	v_mov_b32_e32 v2, 0
	v_add_u32_e32 v41, s4, v39
	v_mov_b32_e32 v42, v37
	s_mov_b32 s11, s77
	v_mov_b32_e32 v3, v2
	v_mov_b32_e32 v4, v2
	v_mov_b32_e32 v5, v2
	v_mov_b32_e32 v6, v2
	v_mov_b32_e32 v7, v2
	v_mov_b32_e32 v8, v2
	v_mov_b32_e32 v9, v2
	v_mov_b32_e32 v10, v2
	v_mov_b32_e32 v11, v2
	v_mov_b32_e32 v12, v2
	v_mov_b32_e32 v13, v2
	v_mov_b32_e32 v14, v2
	v_mov_b32_e32 v15, v2
	v_mov_b32_e32 v16, v2
	v_mov_b32_e32 v17, v2
; #define LAS __attribute__((address_space(3)))
; __device__ __forceinline__ unsigned pk2(float lo, float hi) { const f32x2 v = {lo, hi}; return __builtin_bit_cast(unsigned, __builtin_convertvector(v, bf16x2_t)); }
; #define MFMA32(a, b, c) __builtin_amdgcn_mfma_f32_32x32x16_bf16((a), (b), (c), 0, 0, 0)
; __device__ __forceinline__ void gmlp_task(LAS unsigned char* lds, const Params& p, const bf16_t* P, bf16_t* Y, const float* svg, float* ssb, int l, bool sample, int b, int g, int q, int tid, int wave, int lane, bool load_ws = true) {
;     ...
;             for (int ks = 0; ks < nks; ++ks) {
;                 const s16x4 alo = __builtin_amdgcn_ds_read_tr16_b64_v4i16((LAS s16x4*)(tr + 16 * ks * 72)), ahi = __builtin_amdgcn_ds_read_tr16_b64_v4i16((LAS s16x4*)(tr + (16 * ks + 4) * 72));
;                 const bf16x8 a = __builtin_shufflevector(alo, ahi, 0, 1, 2, 3, 4, 5, 6, 7);
;                 const bf16x8 bw = *(const LAS bf16x8*)(WSL + (32 * it + r) * 136 + 16 * ks + 8 * h);
;                 acc = MFMA32(a, bw, acc);
;             }
;             bf16_t* yp = Y + row * DM + 1024 + g * 64 + 32 * dt + 8 * h;
;             float ss = 0.f;
; #pragma unroll
;             for (int pr = 0; pr < 2; ++pr) {
;                 float a[4], bq[4];
; #pragma unroll
;                 for (int k = 0; k < 4; ++k) { a[k] = acc[8 * pr + k] + bias; bq[k] = acc[8 * pr + 4 + k] + bias; }
; #pragma unroll
;                 for (int k = 0; k < 4; ++k) swap_halves(a[k], bq[k]);
;                 const u32x4 u4 = uw[pr], g4 = gw[pr];
;                 a[0] *= bf_lo(u4.x); a[1] *= bf_hi(u4.x); a[2] *= bf_lo(u4.y); a[3] *= bf_hi(u4.y); bq[0] *= bf_lo(u4.z); bq[1] *= bf_hi(u4.z); bq[2] *= bf_lo(u4.w); bq[3] *= bf_hi(u4.w);
;                 ss += ((a[0] * a[0] + a[1] * a[1]) + (a[2] * a[2] + a[3] * a[3])) + ((bq[0] * bq[0] + bq[1] * bq[1]) + (bq[2] * bq[2] + bq[3] * bq[3]));
;                 u32x4 w; w.x = pk2(a[0] * bf_lo(g4.x), a[1] * bf_hi(g4.x)); w.y = pk2(a[2] * bf_lo(g4.y), a[3] * bf_hi(g4.y));
;                 w.z = pk2(bq[0] * bf_lo(g4.z), bq[1] * bf_hi(g4.z)); w.w = pk2(bq[2] * bf_lo(g4.w), bq[3] * bf_hi(g4.w));
;                 *(u32x4*)(yp + 16 * pr) = w;
;             }
;             ss += __shfl_xor(ss, 32);
;             if (h == 0) ssb[row * 32 + g * 2 + dt] = ss;
.LBB0_497:
	v_add_u32_e32 v43, 0xfffffdc0, v41
	ds_read_b64_tr_b16 v[44:45], v43
	ds_read_b64_tr_b16 v[46:47], v41
	ds_read_b128 v[48:51], v42
	s_add_i32 s11, s11, -1
	v_add_u32_e32 v42, 32, v42
	s_cmp_lg_u32 s11, 0
	v_add_u32_e32 v41, 0x900, v41
	s_waitcnt lgkmcnt(0)
	v_mfma_f32_32x32x16_bf16 v[2:17], v[44:47], v[48:51], v[2:17]
	s_cbranch_scc1 .LBB0_497
	s_nop 10
	v_add_f32_e32 v2, v36, v2
	v_add_f32_e32 v6, v36, v6
	v_add_f32_e32 v3, v36, v3
	v_add_f32_e32 v7, v36, v7
	v_add_f32_e32 v4, v36, v4
	v_add_f32_e32 v8, v36, v8
	v_add_f32_e32 v5, v36, v5
	v_add_f32_e32 v9, v36, v9
	v_permlane32_swap_b32_e32 v2, v6
	v_permlane32_swap_b32_e32 v3, v7
	v_permlane32_swap_b32_e32 v4, v8
	v_permlane32_swap_b32_e32 v5, v9
	s_waitcnt vmcnt(13)
	v_lshlrev_b32_e32 v44, 16, v96
	v_and_b32_e32 v45, 0xffff0000, v96
	v_lshlrev_b32_e32 v30, 16, v97
	v_and_b32_e32 v31, 0xffff0000, v97
	v_pk_mul_f32 v[2:3], v[44:45], v[2:3]
	s_waitcnt vmcnt(12)
	v_lshlrev_b32_e32 v46, 16, v92
	v_and_b32_e32 v47, 0xffff0000, v92
	v_pk_mul_f32 v[4:5], v[30:31], v[4:5]
	v_lshlrev_b32_e32 v26, 16, v93
	v_and_b32_e32 v27, 0xffff0000, v93
	v_pk_mul_f32 v[44:45], v[2:3], v[2:3]
	v_pk_mul_f32 v[2:3], v[2:3], v[46:47]
	v_pk_mul_f32 v[30:31], v[4:5], v[4:5]
	v_pk_mul_f32 v[4:5], v[4:5], v[26:27]
	v_cvt_pk_bf16_f32 v2, v2, v3
	v_cvt_pk_bf16_f32 v3, v4, v5
	v_lshlrev_b32_e32 v4, 16, v98
	v_and_b32_e32 v5, 0xffff0000, v98
	v_lshlrev_b64 v[42:43], 12, v[0:1]
	v_pk_mul_f32 v[4:5], v[4:5], v[6:7]
	v_lshlrev_b32_e32 v6, 16, v94
	v_and_b32_e32 v7, 0xffff0000, v94
	v_lshl_add_u64 v[42:43], s[36:37], 0, v[42:43]
	v_pk_mul_f32 v[26:27], v[4:5], v[4:5]
	v_pk_mul_f32 v[4:5], v[4:5], v[6:7]
	v_lshlrev_b32_e32 v6, 16, v99
	v_and_b32_e32 v7, 0xffff0000, v99
	v_lshl_add_u64 v[42:43], s[0:1], 1, v[42:43]
	v_pk_mul_f32 v[6:7], v[6:7], v[8:9]
	v_lshlrev_b32_e32 v28, 16, v95
	v_and_b32_e32 v29, 0xffff0000, v95
	v_lshl_add_u64 v[42:43], v[42:43], 0, s[44:45]
	v_pk_mul_f32 v[8:9], v[6:7], v[6:7]
	v_pk_mul_f32 v[6:7], v[6:7], v[28:29]
	v_lshl_add_u64 v[42:43], v[34:35], 1, v[42:43]
	v_cvt_pk_bf16_f32 v4, v4, v5
	v_cvt_pk_bf16_f32 v5, v6, v7
	global_store_dwordx4 v[42:43], v[2:5], off offset:2048
	v_add_f32_e32 v6, v36, v14
	v_add_f32_e32 v7, v36, v15
	v_add_f32_e32 v2, v36, v10
	v_add_f32_e32 v3, v36, v11
	s_nop 0
	v_permlane32_swap_b32_e32 v2, v6
	v_permlane32_swap_b32_e32 v3, v7
	s_waitcnt vmcnt(12)
	v_lshlrev_b32_e32 v4, 16, v88
	v_and_b32_e32 v5, 0xffff0000, v88
	v_pk_mul_f32 v[2:3], v[4:5], v[2:3]
	s_waitcnt vmcnt(11)
	v_lshlrev_b32_e32 v4, 16, v84
	v_and_b32_e32 v5, 0xffff0000, v84
	v_add_f32_e32 v10, v36, v12
	v_add_f32_e32 v12, v36, v16
	v_add_f32_e32 v11, v36, v13
	v_add_f32_e32 v13, v36, v17
	v_pk_mul_f32 v[14:15], v[2:3], v[2:3]
	v_pk_mul_f32 v[2:3], v[2:3], v[4:5]
	v_permlane32_swap_b32_e32 v10, v12
	v_permlane32_swap_b32_e32 v11, v13
	v_cvt_pk_bf16_f32 v4, v2, v3
	v_lshlrev_b32_e32 v2, 16, v89
	v_and_b32_e32 v3, 0xffff0000, v89
	v_lshlrev_b32_e32 v16, 16, v85
	v_pk_mul_f32 v[2:3], v[2:3], v[10:11]
	v_and_b32_e32 v17, 0xffff0000, v85
	v_pk_mul_f32 v[10:11], v[2:3], v[2:3]
	v_pk_mul_f32 v[2:3], v[2:3], v[16:17]
	s_nop 0
	v_cvt_pk_bf16_f32 v5, v2, v3
	v_lshlrev_b32_e32 v2, 16, v90
	v_and_b32_e32 v3, 0xffff0000, v90
	v_pk_mul_f32 v[2:3], v[2:3], v[6:7]
	v_lshlrev_b32_e32 v6, 16, v86
	v_and_b32_e32 v7, 0xffff0000, v86
	v_pk_mul_f32 v[16:17], v[2:3], v[2:3]
	v_pk_mul_f32 v[2:3], v[2:3], v[6:7]
	v_add_f32_e32 v7, v8, v9
	v_cvt_pk_bf16_f32 v6, v2, v3
	v_lshlrev_b32_e32 v2, 16, v91
	v_and_b32_e32 v3, 0xffff0000, v91
	v_pk_mul_f32 v[12:13], v[2:3], v[12:13]
	v_add_f32_e32 v8, v26, v27
	v_pk_mul_f32 v[2:3], v[12:13], v[12:13]
	v_add_f32_e32 v7, v8, v7
	v_add_f32_e32 v8, v30, v31
	v_add_f32_e32 v9, v44, v45
	v_add_f32_e32 v8, v9, v8
	v_add_f32_e32 v2, v2, v3
	v_add_f32_e32 v3, v16, v17
	v_add_f32_e32 v7, v8, v7
	v_add_f32_e32 v2, v3, v2
	v_add_f32_e32 v3, v10, v11
	v_add_f32_e32 v8, v14, v15
	v_add_f32_e32 v3, v8, v3
	v_add_f32_e32 v2, v3, v2
	v_add_f32_e32 v2, v7, v2
	ds_bpermute_b32 v3, v40, v2
	v_lshlrev_b32_e32 v8, 16, v87
	v_and_b32_e32 v9, 0xffff0000, v87
	v_pk_mul_f32 v[8:9], v[12:13], v[8:9]
	s_nop 0
	v_cvt_pk_bf16_f32 v7, v8, v9
	global_store_dwordx4 v[42:43], v[4:7], off offset:2080
	s_and_saveexec_b64 s[12:13], s[40:41]
	s_cbranch_execz .LBB0_500
	v_lshlrev_b64 v[4:5], 7, v[0:1]
	v_lshl_add_u64 v[4:5], s[16:17], 0, v[4:5]
	s_waitcnt lgkmcnt(0)
	v_add_f32_e32 v0, v2, v3
	global_store_dword v[4:5], v0, off
.LBB0_500:
	s_or_b64 exec, exec, s[12:13]
	v_add_u32_e32 v0, s10, v38
	s_waitcnt lgkmcnt(0)
	v_mov_b64_e32 v[2:3], s[68:69]
	v_mad_u64_u32 v[2:3], s[10:11], v0, s73, v[2:3]
	v_lshl_add_u64 v[2:3], s[0:1], 1, v[2:3]
	v_lshl_add_u64 v[2:3], v[2:3], 0, s[44:45]
	v_lshl_add_u64 v[2:3], v[34:35], 1, v[2:3]
	s_mov_b64 s[4:5], 0x1400
	v_add_co_u32_e32 v8, vcc, 0x1000, v2
	v_lshl_add_u64 v[4:5], v[2:3], 0, s[4:5]
	s_mov_b64 s[4:5], 0x2400
	v_addc_co_u32_e32 v9, vcc, 0, v3, vcc
	v_lshl_add_u64 v[6:7], v[2:3], 0, s[4:5]
	v_add_co_u32_e32 v2, vcc, 0x2000, v2
	v_readlane_b32 s4, v254, 59
	s_nop 0
	v_addc_co_u32_e32 v3, vcc, 0, v3, vcc
	v_mov_b32_e32 v2, 0
	v_add_u32_e32 v38, s4, v39
	s_mov_b32 s10, s77
	v_mov_b32_e32 v3, v2
	v_mov_b32_e32 v4, v2
	v_mov_b32_e32 v5, v2
	v_mov_b32_e32 v6, v2
	v_mov_b32_e32 v7, v2
	v_mov_b32_e32 v8, v2
	v_mov_b32_e32 v9, v2
	v_mov_b32_e32 v10, v2
	v_mov_b32_e32 v11, v2
	v_mov_b32_e32 v12, v2
	v_mov_b32_e32 v13, v2
	v_mov_b32_e32 v14, v2
	v_mov_b32_e32 v15, v2
	v_mov_b32_e32 v16, v2
	v_mov_b32_e32 v17, v2
; #define LAS __attribute__((address_space(3)))
; __device__ __forceinline__ void gmlp_task(LAS unsigned char* lds, const Params& p, const bf16_t* P, bf16_t* Y, const float* svg, float* ssb, int l, bool sample, int b, int g, int q, int tid, int wave, int lane, bool load_ws = true) {
;     ...
; #pragma unroll
;         for (int k = 0; k < 2; ++k) {
;             const int id = tid + 512 * k;
;             if (id >= L * 8) continue;
;             const int ch = id & 7, j = id >> 3;
;             const f32x2 mr = MUR[sub * 128 + j];
;             const float mean = mr.x, rstd = mr.y;
;             const u32x4 w = wraw[sub][k];
;     ...
;             for (int ks = 0; ks < nks; ++ks) {
;                 const s16x4 alo = __builtin_amdgcn_ds_read_tr16_b64_v4i16((LAS s16x4*)(tr + 16 * ks * 72)), ahi = __builtin_amdgcn_ds_read_tr16_b64_v4i16((LAS s16x4*)(tr + (16 * ks + 4) * 72));
;                 const bf16x8 a = __builtin_shufflevector(alo, ahi, 0, 1, 2, 3, 4, 5, 6, 7);
;                 const bf16x8 bw = *(const LAS bf16x8*)(WSL + (32 * it + r) * 136 + 16 * ks + 8 * h);
;                 acc = MFMA32(a, bw, acc);
;             }
;             bf16_t* yp = Y + row * DM + 1024 + g * 64 + 32 * dt + 8 * h;
;             float ss = 0.f;
; #pragma unroll
;             for (int pr = 0; pr < 2; ++pr) {
;                 float a[4], bq[4];
; #pragma unroll
;                 for (int k = 0; k < 4; ++k) { a[k] = acc[8 * pr + k] + bias; bq[k] = acc[8 * pr + 4 + k] + bias; }
; #pragma unroll
;                 for (int k = 0; k < 4; ++k) swap_halves(a[k], bq[k]);
;                 const u32x4 u4 = uw[pr], g4 = gw[pr];
;                 a[0] *= bf_lo(u4.x); a[1] *= bf_hi(u4.x); a[2] *= bf_lo(u4.y); a[3] *= bf_hi(u4.y); bq[0] *= bf_lo(u4.z); bq[1] *= bf_hi(u4.z); bq[2] *= bf_lo(u4.w); bq[3] *= bf_hi(u4.w);
;                 ss += ((a[0] * a[0] + a[1] * a[1]) + (a[2] * a[2] + a[3] * a[3])) + ((bq[0] * bq[0] + bq[1] * bq[1]) + (bq[2] * bq[2] + bq[3] * bq[3]));
;                 u32x4 w; w.x = pk2(a[0] * bf_lo(g4.x), a[1] * bf_hi(g4.x)); w.y = pk2(a[2] * bf_lo(g4.y), a[3] * bf_hi(g4.y));
;                 w.z = pk2(bq[0] * bf_lo(g4.z), bq[1] * bf_hi(g4.z)); w.w = pk2(bq[2] * bf_lo(g4.w), bq[3] * bf_hi(g4.w));
;                 *(u32x4*)(yp + 16 * pr) = w;
;             }
;             ss += __shfl_xor(ss, 32);
;             if (h == 0) ssb[row * 32 + g * 2 + dt] = ss;
.LBB0_501:
	v_add_u32_e32 v39, 0xfffffdc0, v38
	ds_read_b64_tr_b16 v[42:43], v39
	ds_read_b64_tr_b16 v[44:45], v38
	ds_read_b128 v[46:49], v37
	s_add_i32 s10, s10, -1
	v_add_u32_e32 v37, 32, v37
	s_cmp_lg_u32 s10, 0
	v_add_u32_e32 v38, 0x900, v38
	s_waitcnt lgkmcnt(0)
	v_mfma_f32_32x32x16_bf16 v[2:17], v[42:45], v[46:49], v[2:17]
	s_cbranch_scc1 .LBB0_501
	v_lshlrev_b64 v[38:39], 12, v[0:1]
	v_lshl_add_u64 v[38:39], s[36:37], 0, v[38:39]
	v_lshl_add_u64 v[38:39], s[0:1], 1, v[38:39]
	s_nop 7
	v_add_f32_e32 v2, v36, v2
	v_add_f32_e32 v6, v36, v6
	v_add_f32_e32 v3, v36, v3
	v_add_f32_e32 v7, v36, v7
	v_add_f32_e32 v4, v36, v4
	v_add_f32_e32 v8, v36, v8
	v_add_f32_e32 v5, v36, v5
	v_add_f32_e32 v9, v36, v9
	v_lshl_add_u64 v[38:39], v[38:39], 0, s[44:45]
	v_permlane32_swap_b32_e32 v2, v6
	v_permlane32_swap_b32_e32 v3, v7
	v_permlane32_swap_b32_e32 v4, v8
	v_permlane32_swap_b32_e32 v5, v9
	v_lshl_add_u64 v[34:35], v[34:35], 1, v[38:39]
	s_waitcnt vmcnt(12)
	v_lshlrev_b32_e32 v38, 16, v112
	v_and_b32_e32 v39, 0xffff0000, v112
	v_lshlrev_b32_e32 v30, 16, v113
	v_and_b32_e32 v31, 0xffff0000, v113
	v_pk_mul_f32 v[2:3], v[38:39], v[2:3]
	s_waitcnt vmcnt(11)
	v_lshlrev_b32_e32 v42, 16, v108
	v_and_b32_e32 v43, 0xffff0000, v108
	v_pk_mul_f32 v[4:5], v[30:31], v[4:5]
	v_lshlrev_b32_e32 v26, 16, v109
	v_and_b32_e32 v27, 0xffff0000, v109
	v_pk_mul_f32 v[38:39], v[2:3], v[2:3]
	v_pk_mul_f32 v[2:3], v[2:3], v[42:43]
	v_pk_mul_f32 v[30:31], v[4:5], v[4:5]
	v_pk_mul_f32 v[4:5], v[4:5], v[26:27]
	v_cvt_pk_bf16_f32 v2, v2, v3
	v_cvt_pk_bf16_f32 v3, v4, v5
	v_lshlrev_b32_e32 v4, 16, v114
	v_and_b32_e32 v5, 0xffff0000, v114
	v_pk_mul_f32 v[4:5], v[4:5], v[6:7]
	v_lshlrev_b32_e32 v6, 16, v110
	v_and_b32_e32 v7, 0xffff0000, v110
	v_pk_mul_f32 v[26:27], v[4:5], v[4:5]
	v_pk_mul_f32 v[4:5], v[4:5], v[6:7]
	v_lshlrev_b32_e32 v6, 16, v115
	v_and_b32_e32 v7, 0xffff0000, v115
	v_pk_mul_f32 v[6:7], v[6:7], v[8:9]
	v_lshlrev_b32_e32 v28, 16, v111
	v_and_b32_e32 v29, 0xffff0000, v111
	v_pk_mul_f32 v[8:9], v[6:7], v[6:7]
	v_pk_mul_f32 v[6:7], v[6:7], v[28:29]
	v_cvt_pk_bf16_f32 v4, v4, v5
	v_cvt_pk_bf16_f32 v5, v6, v7
	global_store_dwordx4 v[34:35], v[2:5], off offset:2048
	v_add_f32_e32 v6, v36, v14
	v_add_f32_e32 v7, v36, v15
	v_add_f32_e32 v2, v36, v10
	v_add_f32_e32 v3, v36, v11
	s_nop 0
	v_permlane32_swap_b32_e32 v2, v6
	v_permlane32_swap_b32_e32 v3, v7
	s_waitcnt vmcnt(11)
	v_lshlrev_b32_e32 v4, 16, v104
	v_and_b32_e32 v5, 0xffff0000, v104
	v_pk_mul_f32 v[2:3], v[4:5], v[2:3]
	s_waitcnt vmcnt(10)
	v_lshlrev_b32_e32 v4, 16, v100
	v_and_b32_e32 v5, 0xffff0000, v100
	v_add_f32_e32 v10, v36, v12
	v_add_f32_e32 v12, v36, v16
	v_add_f32_e32 v11, v36, v13
	v_add_f32_e32 v13, v36, v17
	v_pk_mul_f32 v[14:15], v[2:3], v[2:3]
	v_pk_mul_f32 v[2:3], v[2:3], v[4:5]
	v_permlane32_swap_b32_e32 v10, v12
	v_permlane32_swap_b32_e32 v11, v13
	v_cvt_pk_bf16_f32 v4, v2, v3
	v_lshlrev_b32_e32 v2, 16, v105
	v_and_b32_e32 v3, 0xffff0000, v105
	v_lshlrev_b32_e32 v16, 16, v101
	v_pk_mul_f32 v[2:3], v[2:3], v[10:11]
	v_and_b32_e32 v17, 0xffff0000, v101
	v_pk_mul_f32 v[10:11], v[2:3], v[2:3]
	v_pk_mul_f32 v[2:3], v[2:3], v[16:17]
	s_nop 0
	v_cvt_pk_bf16_f32 v5, v2, v3
	v_lshlrev_b32_e32 v2, 16, v106
	v_and_b32_e32 v3, 0xffff0000, v106
	v_pk_mul_f32 v[2:3], v[2:3], v[6:7]
	v_lshlrev_b32_e32 v6, 16, v102
	v_and_b32_e32 v7, 0xffff0000, v102
	v_pk_mul_f32 v[16:17], v[2:3], v[2:3]
	v_pk_mul_f32 v[2:3], v[2:3], v[6:7]
	v_add_f32_e32 v7, v8, v9
	v_cvt_pk_bf16_f32 v6, v2, v3
	v_lshlrev_b32_e32 v2, 16, v107
	v_and_b32_e32 v3, 0xffff0000, v107
	v_pk_mul_f32 v[12:13], v[2:3], v[12:13]
	v_add_f32_e32 v8, v26, v27
	v_pk_mul_f32 v[2:3], v[12:13], v[12:13]
	v_add_f32_e32 v7, v8, v7
	v_add_f32_e32 v8, v30, v31
	v_add_f32_e32 v9, v38, v39
	v_add_f32_e32 v8, v9, v8
	v_add_f32_e32 v2, v2, v3
	v_add_f32_e32 v3, v16, v17
	v_add_f32_e32 v7, v8, v7
	v_add_f32_e32 v2, v3, v2
	v_add_f32_e32 v3, v10, v11
	v_add_f32_e32 v8, v14, v15
	v_add_f32_e32 v3, v8, v3
	v_add_f32_e32 v2, v3, v2
	v_add_f32_e32 v2, v7, v2
	ds_bpermute_b32 v3, v40, v2
	v_lshlrev_b32_e32 v8, 16, v103
	v_and_b32_e32 v9, 0xffff0000, v103
	v_pk_mul_f32 v[8:9], v[12:13], v[8:9]
	s_nop 0
	v_cvt_pk_bf16_f32 v7, v8, v9
	global_store_dwordx4 v[34:35], v[4:7], off offset:2080
	s_and_saveexec_b64 s[0:1], s[40:41]
	s_cbranch_execz .LBB0_448
	v_lshlrev_b64 v[4:5], 7, v[0:1]
	v_lshl_add_u64 v[4:5], s[16:17], 0, v[4:5]
	s_waitcnt lgkmcnt(0)
	v_add_f32_e32 v0, v2, v3
	global_store_dword v[4:5], v0, off
	s_branch .LBB0_448
.LBB0_504:
	v_add_u32_e32 v32, 0x1a800, v31
	ds_read_b64 v[32:33], v32
	v_lshlrev_b32_e32 v40, 16, v26
	v_and_b32_e32 v41, 0xffff0000, v26
	v_lshlrev_b32_e32 v26, 16, v27
	v_and_b32_e32 v27, 0xffff0000, v27
	v_lshlrev_b32_e32 v43, 16, v28
	v_and_b32_e32 v44, 0xffff0000, v28
	v_lshlrev_b32_e32 v62, 16, v29
	v_and_b32_e32 v63, 0xffff0000, v29
	s_waitcnt lgkmcnt(0)
	v_sub_f32_e32 v27, v27, v32
	v_sub_f32_e32 v26, v26, v32
	v_sub_f32_e32 v29, v41, v32
	v_sub_f32_e32 v28, v40, v32
	v_pk_mul_f32 v[28:29], v[32:33], v[28:29] op_sel:[1,0]
	v_pk_mul_f32 v[26:27], v[32:33], v[26:27] op_sel:[1,0]
	s_waitcnt vmcnt(0)
	v_pk_fma_f32 v[40:41], v[198:199], v[26:27], v[206:207]
	v_pk_fma_f32 v[26:27], v[196:197], v[28:29], v[204:205]
	v_sub_f32_e32 v29, v63, v32
	v_sub_f32_e32 v28, v62, v32
	v_sub_f32_e32 v51, v44, v32
	v_sub_f32_e32 v50, v43, v32
	v_pk_mul_f32 v[50:51], v[32:33], v[50:51] op_sel:[1,0]
	v_pk_mul_f32 v[28:29], v[32:33], v[28:29] op_sel:[1,0]
	v_cvt_pk_bf16_f32 v26, v26, v27
	v_pk_fma_f32 v[32:33], v[194:195], v[28:29], v[202:203]
	v_pk_fma_f32 v[28:29], v[192:193], v[50:51], v[200:201]
	v_cvt_pk_bf16_f32 v27, v40, v41
	v_cvt_pk_bf16_f32 v28, v28, v29
	v_cvt_pk_bf16_f32 v29, v32, v33
	v_mad_u64_u32 v[32:33], s[18:19], v30, s89, v[0:1]
	ds_write_b128 v32, v[26:29]
	s_or_b64 exec, exec, s[16:17]
	s_and_saveexec_b64 s[16:17], s[42:43]
	s_cbranch_execz .LBB0_482
; #define LAS __attribute__((address_space(3)))
; __device__ __forceinline__ u32x4 pack8(f32x4 a, f32x4 b) { u32x4 w; w.x = pk2(a[0], a[1]); w.y = pk2(a[2], a[3]); w.z = pk2(b[0], b[1]); w.w = pk2(b[2], b[3]); return w; }
; __device__ __forceinline__ void gmlp_task(LAS unsigned char* lds, const Params& p, const bf16_t* P, bf16_t* Y, const float* svg, float* ssb, int l, bool sample, int b, int g, int q, int tid, int wave, int lane, bool load_ws = true) {
;     ...
; #pragma unroll
;         for (int k = 0; k < 2; ++k) {
;             const int id = tid + 512 * k;
;             if (id >= L * 8) continue;
;             const int ch = id & 7, j = id >> 3;
;             const f32x2 mr = MUR[sub * 128 + j];
;             const float mean = mr.x, rstd = mr.y;
;             const u32x4 w = wraw[sub][k];
;             const f32x4 g0 = *(const f32x4*)(lg + ch * 8), g1 = *(const f32x4*)(lg + ch * 8 + 4), b0 = *(const f32x4*)(lb + ch * 8), b1 = *(const f32x4*)(lb + ch * 8 + 4);
;             f32x4 v0 = (f32x4){bf_lo(w.x), bf_hi(w.x), bf_lo(w.y), bf_hi(w.y)}, v1 = (f32x4){bf_lo(w.z), bf_hi(w.z), bf_lo(w.w), bf_hi(w.w)};
;             v0 = (v0 - mean) * rstd * g0 + b0; v1 = (v1 - mean) * rstd * g1 + b1;
;             if (sample) { float* dst = p.out + OUT_VGS + ((((size_t)l * 32 + cidx) * 32 + j) * 16 + g) * 64 + ch * 8; *(f32x4*)dst = v0; *(f32x4*)(dst + 4) = v1; }
;             *(LAS u32x4*)(VGT + j * 72 + ch * 8) = pack8(v0, v1);
.LBB0_505:
	v_add_u32_e32 v26, 0x1ac00, v39
	ds_read_b64 v[32:33], v26
	v_lshlrev_b32_e32 v40, 16, v22
	v_and_b32_e32 v41, 0xffff0000, v22
	v_lshlrev_b32_e32 v22, 16, v23
	v_and_b32_e32 v23, 0xffff0000, v23
	v_lshlrev_b32_e32 v43, 16, v24
	v_and_b32_e32 v44, 0xffff0000, v24
	v_lshlrev_b32_e32 v58, 16, v25
	v_and_b32_e32 v59, 0xffff0000, v25
	s_waitcnt lgkmcnt(0)
	v_sub_f32_e32 v23, v23, v32
	v_sub_f32_e32 v22, v22, v32
	v_sub_f32_e32 v25, v41, v32
	v_sub_f32_e32 v24, v40, v32
	v_pk_mul_f32 v[24:25], v[32:33], v[24:25] op_sel:[1,0]
	v_pk_mul_f32 v[22:23], v[32:33], v[22:23] op_sel:[1,0]
	s_waitcnt vmcnt(0)
	v_pk_fma_f32 v[40:41], v[198:199], v[22:23], v[206:207]
	v_pk_fma_f32 v[22:23], v[196:197], v[24:25], v[204:205]
	v_sub_f32_e32 v25, v59, v32
	v_sub_f32_e32 v24, v58, v32
	v_sub_f32_e32 v47, v44, v32
	v_sub_f32_e32 v46, v43, v32
	v_pk_mul_f32 v[46:47], v[32:33], v[46:47] op_sel:[1,0]
	v_pk_mul_f32 v[24:25], v[32:33], v[24:25] op_sel:[1,0]
	v_cvt_pk_bf16_f32 v22, v22, v23
	v_pk_fma_f32 v[28:29], v[194:195], v[24:25], v[202:203]
	v_pk_fma_f32 v[24:25], v[192:193], v[46:47], v[200:201]
	v_cvt_pk_bf16_f32 v23, v40, v41
	v_cvt_pk_bf16_f32 v24, v24, v25
	v_cvt_pk_bf16_f32 v25, v28, v29
	v_mad_u64_u32 v[26:27], s[18:19], v38, s89, v[0:1]
	ds_write_b128 v26, v[22:25] offset:18432
	s_or_b64 exec, exec, s[16:17]
	s_and_saveexec_b64 s[16:17], s[40:41]
	s_cbranch_execz .LBB0_483
.LBB0_506:
	v_add_u32_e32 v22, 0x1ac00, v31
	ds_read_b64 v[32:33], v22
	v_lshlrev_b32_e32 v40, 16, v18
	v_and_b32_e32 v41, 0xffff0000, v18
	v_lshlrev_b32_e32 v18, 16, v19
	v_and_b32_e32 v19, 0xffff0000, v19
	v_lshlrev_b32_e32 v43, 16, v20
	v_and_b32_e32 v44, 0xffff0000, v20
	v_lshlrev_b32_e32 v54, 16, v21
	v_and_b32_e32 v55, 0xffff0000, v21
	s_waitcnt lgkmcnt(0)
	v_sub_f32_e32 v19, v19, v32
	v_sub_f32_e32 v18, v18, v32
	v_sub_f32_e32 v21, v41, v32
	v_sub_f32_e32 v20, v40, v32
	v_pk_mul_f32 v[20:21], v[32:33], v[20:21] op_sel:[1,0]
	v_pk_mul_f32 v[18:19], v[32:33], v[18:19] op_sel:[1,0]
	s_waitcnt vmcnt(0)
	v_pk_fma_f32 v[28:29], v[198:199], v[18:19], v[206:207]
	v_pk_fma_f32 v[18:19], v[196:197], v[20:21], v[204:205]
	v_sub_f32_e32 v21, v55, v32
	v_sub_f32_e32 v20, v54, v32
	v_sub_f32_e32 v27, v44, v32
	v_sub_f32_e32 v26, v43, v32
	v_pk_mul_f32 v[26:27], v[32:33], v[26:27] op_sel:[1,0]
	v_pk_mul_f32 v[20:21], v[32:33], v[20:21] op_sel:[1,0]
	v_cvt_pk_bf16_f32 v18, v18, v19
	v_pk_fma_f32 v[24:25], v[194:195], v[20:21], v[202:203]
	v_pk_fma_f32 v[20:21], v[192:193], v[26:27], v[200:201]
	v_cvt_pk_bf16_f32 v19, v28, v29
	v_cvt_pk_bf16_f32 v20, v20, v21
	v_cvt_pk_bf16_f32 v21, v24, v25
	v_mad_u64_u32 v[22:23], s[18:19], v30, s89, v[0:1]
	ds_write_b128 v22, v[18:21] offset:18432
	s_or_b64 exec, exec, s[16:17]
	s_and_saveexec_b64 s[16:17], s[42:43]
	s_cbranch_execz .LBB0_484
.LBB0_507:
	v_add_u32_e32 v18, 0x1b000, v39
	ds_read_b64 v[32:33], v18
	v_lshlrev_b32_e32 v40, 16, v14
	v_and_b32_e32 v41, 0xffff0000, v14
	v_lshlrev_b32_e32 v14, 16, v15
	v_and_b32_e32 v15, 0xffff0000, v15
	v_lshlrev_b32_e32 v43, 16, v16
	v_and_b32_e32 v44, 0xffff0000, v16
	v_lshlrev_b32_e32 v50, 16, v17
	v_and_b32_e32 v51, 0xffff0000, v17
	s_waitcnt lgkmcnt(0)
	v_sub_f32_e32 v15, v15, v32
	v_sub_f32_e32 v14, v14, v32
	v_sub_f32_e32 v17, v41, v32
	v_sub_f32_e32 v16, v40, v32
	v_pk_mul_f32 v[16:17], v[32:33], v[16:17] op_sel:[1,0]
	v_pk_mul_f32 v[14:15], v[32:33], v[14:15] op_sel:[1,0]
	s_waitcnt vmcnt(0)
	v_pk_fma_f32 v[24:25], v[198:199], v[14:15], v[206:207]
	v_pk_fma_f32 v[14:15], v[196:197], v[16:17], v[204:205]
	v_sub_f32_e32 v17, v51, v32
	v_sub_f32_e32 v16, v50, v32
	v_sub_f32_e32 v23, v44, v32
	v_sub_f32_e32 v22, v43, v32
	v_pk_mul_f32 v[22:23], v[32:33], v[22:23] op_sel:[1,0]
	v_pk_mul_f32 v[16:17], v[32:33], v[16:17] op_sel:[1,0]
	v_cvt_pk_bf16_f32 v14, v14, v15
	v_pk_fma_f32 v[20:21], v[194:195], v[16:17], v[202:203]
	v_pk_fma_f32 v[16:17], v[192:193], v[22:23], v[200:201]
	v_cvt_pk_bf16_f32 v15, v24, v25
	v_cvt_pk_bf16_f32 v16, v16, v17
	v_cvt_pk_bf16_f32 v17, v20, v21
	v_mad_u64_u32 v[18:19], s[18:19], v38, s89, v[0:1]
	ds_write_b128 v18, v[14:17] offset:36864
	s_or_b64 exec, exec, s[16:17]
	s_and_saveexec_b64 s[16:17], s[40:41]
	s_cbranch_execz .LBB0_485
.LBB0_508:
	v_add_u32_e32 v14, 0x1b000, v31
	ds_read_b64 v[32:33], v14
	v_lshlrev_b32_e32 v40, 16, v10
	v_and_b32_e32 v41, 0xffff0000, v10
	v_lshlrev_b32_e32 v10, 16, v11
	v_and_b32_e32 v11, 0xffff0000, v11
	v_lshlrev_b32_e32 v43, 16, v12
	v_and_b32_e32 v44, 0xffff0000, v12
	v_lshlrev_b32_e32 v46, 16, v13
	v_and_b32_e32 v47, 0xffff0000, v13
	s_waitcnt lgkmcnt(0)
	v_sub_f32_e32 v11, v11, v32
	v_sub_f32_e32 v10, v10, v32
	v_sub_f32_e32 v13, v41, v32
	v_sub_f32_e32 v12, v40, v32
	v_pk_mul_f32 v[12:13], v[32:33], v[12:13] op_sel:[1,0]
	v_pk_mul_f32 v[10:11], v[32:33], v[10:11] op_sel:[1,0]
	s_waitcnt vmcnt(0)
	v_pk_fma_f32 v[20:21], v[198:199], v[10:11], v[206:207]
	v_pk_fma_f32 v[10:11], v[196:197], v[12:13], v[204:205]
	v_sub_f32_e32 v13, v47, v32
	v_sub_f32_e32 v12, v46, v32
	v_sub_f32_e32 v19, v44, v32
	v_sub_f32_e32 v18, v43, v32
	v_pk_mul_f32 v[18:19], v[32:33], v[18:19] op_sel:[1,0]
	v_pk_mul_f32 v[12:13], v[32:33], v[12:13] op_sel:[1,0]
	v_cvt_pk_bf16_f32 v10, v10, v11
	v_pk_fma_f32 v[16:17], v[194:195], v[12:13], v[202:203]
	v_pk_fma_f32 v[12:13], v[192:193], v[18:19], v[200:201]
	v_cvt_pk_bf16_f32 v11, v20, v21
	v_cvt_pk_bf16_f32 v12, v12, v13
	v_cvt_pk_bf16_f32 v13, v16, v17
	v_mad_u64_u32 v[14:15], s[18:19], v30, s89, v[0:1]
	ds_write_b128 v14, v[10:13] offset:36864
	s_or_b64 exec, exec, s[16:17]
	s_and_saveexec_b64 s[16:17], s[42:43]
	s_cbranch_execz .LBB0_486
.LBB0_509:
	v_add_u32_e32 v10, 0x1b400, v39
	ds_read_b64 v[26:27], v10
	v_lshlrev_b32_e32 v28, 16, v6
	v_and_b32_e32 v29, 0xffff0000, v6
	v_lshlrev_b32_e32 v6, 16, v7
	v_and_b32_e32 v7, 0xffff0000, v7
	v_lshlrev_b32_e32 v32, 16, v8
	v_and_b32_e32 v33, 0xffff0000, v8
	v_lshlrev_b32_e32 v39, 16, v9
	v_and_b32_e32 v40, 0xffff0000, v9
	s_waitcnt lgkmcnt(0)
	v_sub_f32_e32 v7, v7, v26
	v_sub_f32_e32 v6, v6, v26
	v_sub_f32_e32 v9, v29, v26
	v_sub_f32_e32 v8, v28, v26
	v_pk_mul_f32 v[8:9], v[26:27], v[8:9] op_sel:[1,0]
	v_pk_mul_f32 v[6:7], v[26:27], v[6:7] op_sel:[1,0]
	s_waitcnt vmcnt(0)
	v_pk_fma_f32 v[16:17], v[198:199], v[6:7], v[206:207]
	v_pk_fma_f32 v[6:7], v[196:197], v[8:9], v[204:205]
	v_sub_f32_e32 v9, v40, v26
	v_sub_f32_e32 v8, v39, v26
	v_sub_f32_e32 v15, v33, v26
	v_sub_f32_e32 v14, v32, v26
	v_pk_mul_f32 v[14:15], v[26:27], v[14:15] op_sel:[1,0]
	v_pk_mul_f32 v[8:9], v[26:27], v[8:9] op_sel:[1,0]
	v_cvt_pk_bf16_f32 v6, v6, v7
	v_pk_fma_f32 v[12:13], v[194:195], v[8:9], v[202:203]
	v_pk_fma_f32 v[8:9], v[192:193], v[14:15], v[200:201]
	v_cvt_pk_bf16_f32 v7, v16, v17
	v_cvt_pk_bf16_f32 v8, v8, v9
	v_cvt_pk_bf16_f32 v9, v12, v13
	v_mad_u64_u32 v[10:11], s[18:19], v38, s89, v[0:1]
	ds_write_b128 v10, v[6:9] offset:55296
	s_or_b64 exec, exec, s[16:17]
	s_and_saveexec_b64 s[16:17], s[40:41]
	s_cbranch_execnz .LBB0_487
	s_branch .LBB0_488
